# attention softmax: cross-half exchanges via v_permlane32_swap instead of ds_bpermute; scan: prefix sums via DPP instead of ds_bpermute
# baseline (speedup 1.0000x reference)
.LBB0_95:
	s_waitcnt vmcnt(6)
	v_mul_f32_e32 v0, 0x3fb8aa3b, v58
	v_exp_f32_e32 v0, v0
	v_add_u32_e32 v58, v73, v106
	s_waitcnt vmcnt(5)
	ds_write_b128 v58, v[6:9]
	v_add_u32_e32 v6, v103, v107
	s_waitcnt vmcnt(4)
	ds_write_b128 v6, v[2:5] offset:17408
	s_waitcnt vmcnt(3)
	ds_write_b128 v6, v[14:17] offset:35840
	v_add_u32_e32 v59, v73, v108
	v_add_u32_e32 v2, v103, v109
	s_and_b64 vcc, exec, s[16:17]
	s_waitcnt vmcnt(2)
	ds_write_b128 v59, v[10:13]
	s_waitcnt vmcnt(1)
	ds_write_b128 v2, v[18:21] offset:17408
	s_waitcnt vmcnt(0)
	ds_write_b128 v6, v[22:25] offset:45056
	s_cbranch_vccnz .LBB0_97
	v_mul_f32_e64 v2, v126, -v0
	s_nop 1
	v_add_f32_dpp v2, v2, v2 row_shr:1 row_mask:0xf bank_mask:0xf
	s_nop 1
	v_add_f32_dpp v2, v2, v2 row_shr:2 row_mask:0xf bank_mask:0xf
	s_nop 1
	v_add_f32_dpp v2, v2, v2 row_shr:4 row_mask:0xf bank_mask:0xf
	s_nop 1
	v_add_f32_dpp v2, v2, v2 row_shr:8 row_mask:0xf bank_mask:0xf
	s_nop 1
	v_add_f32_dpp v2, v2, v2 row_bcast:15 row_mask:0xa bank_mask:0xf
	s_nop 1
	v_add_f32_dpp v2, v2, v2 row_bcast:31 row_mask:0xc bank_mask:0xf
	s_nop 1
	v_readlane_b32 s74, v2, 63
	s_nop 1
	v_sub_f32_e32 v3, s74, v2
	v_mul_f32_e32 v3, 0x3fb8aa3b, v3
	v_exp_f32_e32 v3, v3
	s_nop 0
	v_mul_f32_e32 v3, v126, v3
	ds_write2st64_b32 v104, v2, v3 offset0:212 offset1:214

.LBB0_99:
	s_add_u32 s27, s37, s23
	s_addc_u32 s29, s38, 0
	s_lshl_b32 s19, s88, 2
	s_add_u32 s19, s20, s19
	s_addc_u32 s23, s21, 0
	s_lshl_b32 s18, s18, 2
	s_add_u32 s18, s19, s18
	s_addc_u32 s19, s23, 0
	s_lshl_b32 s23, s91, 2
	s_add_u32 s30, s18, s23
	s_addc_u32 s31, s19, 0
	v_cmp_ne_u32_e64 s[18:19], 1, v60
	s_andn2_b64 vcc, exec, s[24:25]
	s_waitcnt lgkmcnt(0)
	s_barrier
	s_cbranch_vccnz .LBB0_104
	s_waitcnt vmcnt(5)
	ds_write_b128 v58, v[2:5] offset:55296
	v_add_u32_e32 v2, v110, v107
	s_waitcnt vmcnt(4)
	ds_write_b128 v2, v[6:9]
	s_waitcnt vmcnt(3)
	ds_write_b128 v124, v[10:13]
	s_waitcnt vmcnt(2)
	ds_write_b128 v59, v[14:17] offset:55296
	v_add_u32_e32 v2, v110, v109
	s_and_b64 vcc, exec, s[16:17]
	s_waitcnt vmcnt(1)
	ds_write_b128 v2, v[18:21]
	s_waitcnt vmcnt(0)
	ds_write_b128 v124, v[22:25] offset:9216
	s_cbranch_vccnz .LBB0_102
	v_mul_f32_e64 v2, v126, -v0
	s_nop 1
	v_add_f32_dpp v2, v2, v2 row_shr:1 row_mask:0xf bank_mask:0xf
	s_nop 1
	v_add_f32_dpp v2, v2, v2 row_shr:2 row_mask:0xf bank_mask:0xf
	s_nop 1
	v_add_f32_dpp v2, v2, v2 row_shr:4 row_mask:0xf bank_mask:0xf
	s_nop 1
	v_add_f32_dpp v2, v2, v2 row_shr:8 row_mask:0xf bank_mask:0xf
	s_nop 1
	v_add_f32_dpp v2, v2, v2 row_bcast:15 row_mask:0xa bank_mask:0xf
	s_nop 1
	v_add_f32_dpp v2, v2, v2 row_bcast:31 row_mask:0xc bank_mask:0xf
	s_nop 1
	v_readlane_b32 s74, v2, 63
	s_nop 1
	v_sub_f32_e32 v3, s74, v2
	v_mul_f32_e32 v3, 0x3fb8aa3b, v3
	v_exp_f32_e32 v3, v3
	s_nop 0
	v_mul_f32_e32 v3, v126, v3
	ds_write2st64_b32 v111, v2, v3 offset1:2

.LBB0_106:
	s_bitcmp1_b32 s34, 0
	s_cbranch_scc1 .Lscan_B106
	s_bitcmp1_b32 s34, 0
	s_cselect_b32 s19, 0xd800, 0
	s_add_i32 s19, s19, 0
	v_lshl_add_u32 v58, v71, 1, s19
	v_lshl_add_u32 v59, v102, 1, s19
	v_add_u32_e32 v60, v58, v106
	s_waitcnt vmcnt(19)
	ds_write_b128 v60, v[2:5]
	v_add_u32_e32 v60, v59, v107
	v_add_u32_e32 v58, v58, v108
	s_waitcnt vmcnt(18)
	ds_write_b128 v60, v[6:9] offset:17408
	s_waitcnt vmcnt(17)
	ds_write_b128 v60, v[10:13] offset:35840
	s_waitcnt vmcnt(16)
	ds_write_b128 v58, v[14:17]
	v_add_u32_e32 v58, v59, v109
	s_and_b64 vcc, exec, s[16:17]
	s_waitcnt vmcnt(15)
	ds_write_b128 v58, v[18:21] offset:17408
	s_waitcnt vmcnt(14)
	ds_write_b128 v60, v[22:25] offset:45056
	s_cbranch_vccnz .LBB0_108
	v_mul_f32_e64 v58, v126, -v0
	s_nop 1
	v_add_f32_dpp v58, v58, v58 row_shr:1 row_mask:0xf bank_mask:0xf
	s_nop 1
	v_add_f32_dpp v58, v58, v58 row_shr:2 row_mask:0xf bank_mask:0xf
	s_nop 1
	v_add_f32_dpp v58, v58, v58 row_shr:4 row_mask:0xf bank_mask:0xf
	s_nop 1
	v_add_f32_dpp v58, v58, v58 row_shr:8 row_mask:0xf bank_mask:0xf
	s_nop 1
	v_add_f32_dpp v58, v58, v58 row_bcast:15 row_mask:0xa bank_mask:0xf
	s_nop 1
	v_add_f32_dpp v58, v58, v58 row_bcast:31 row_mask:0xc bank_mask:0xf
	s_nop 1
	v_readlane_b32 s74, v58, 63
	s_add_i32 s19, s19, s50
	v_lshl_add_u32 v60, v158, 2, s19
	s_nop 1
	v_sub_f32_e32 v59, s74, v58
	v_mul_f32_e32 v59, 0x3fb8aa3b, v59
	v_exp_f32_e32 v59, v59
	s_nop 0
	v_mul_f32_e32 v59, v126, v59
	ds_write2st64_b32 v60, v58, v59 offset0:212 offset1:214

.Lscan_B106:
	s_bitcmp1_b32 s34, 0
	s_cselect_b32 s19, 0xd800, 0
	s_add_i32 s19, s19, 0
	v_lshl_add_u32 v58, v71, 1, s19
	v_lshl_add_u32 v59, v102, 1, s19
	v_add_u32_e32 v60, v58, v106
	s_waitcnt vmcnt(19)
	ds_write_b128 v60, v[220:223]
	v_add_u32_e32 v60, v59, v107
	v_add_u32_e32 v58, v58, v108
	s_waitcnt vmcnt(18)
	ds_write_b128 v60, v[224:227] offset:17408
	s_waitcnt vmcnt(17)
	ds_write_b128 v60, v[228:231] offset:35840
	s_waitcnt vmcnt(16)
	ds_write_b128 v58, v[232:235]
	v_add_u32_e32 v58, v59, v109
	s_and_b64 vcc, exec, s[16:17]
	s_waitcnt vmcnt(15)
	ds_write_b128 v58, v[236:239] offset:17408
	s_waitcnt vmcnt(14)
	ds_write_b128 v60, v[240:243] offset:45056
	s_cbranch_vccnz .Lscan_B108
	v_mul_f32_e64 v58, v244, -v0
	s_nop 1
	v_add_f32_dpp v58, v58, v58 row_shr:1 row_mask:0xf bank_mask:0xf
	s_nop 1
	v_add_f32_dpp v58, v58, v58 row_shr:2 row_mask:0xf bank_mask:0xf
	s_nop 1
	v_add_f32_dpp v58, v58, v58 row_shr:4 row_mask:0xf bank_mask:0xf
	s_nop 1
	v_add_f32_dpp v58, v58, v58 row_shr:8 row_mask:0xf bank_mask:0xf
	s_nop 1
	v_add_f32_dpp v58, v58, v58 row_bcast:15 row_mask:0xa bank_mask:0xf
	s_nop 1
	v_add_f32_dpp v58, v58, v58 row_bcast:31 row_mask:0xc bank_mask:0xf
	s_nop 1
	v_readlane_b32 s74, v58, 63
	s_add_i32 s19, s19, s50
	v_lshl_add_u32 v60, v158, 2, s19
	s_nop 1
	v_sub_f32_e32 v59, s74, v58
	v_mul_f32_e32 v59, 0x3fb8aa3b, v59
	v_exp_f32_e32 v59, v59
	s_nop 0
	v_mul_f32_e32 v59, v244, v59
	ds_write2st64_b32 v60, v58, v59 offset0:212 offset1:214

.LBB0_409:
	s_cmp_ge_i32 s8, s27
	s_cbranch_scc1 .LBB0_413
	s_mul_hi_u32 s8, s8, 0xaaaaaaab
	s_lshr_b32 s8, s8, 1
	s_mul_i32 s8, s8, 0xfffe1400
	s_add_i32 s8, s28, s8
	v_add_u32_e32 v175, s8, v174
	ds_read_b128 v[176:179], v175
	ds_read_b128 v[180:183], v175 offset:32
	ds_read_b128 v[184:187], v175 offset:20992
	ds_read_b128 v[188:191], v175 offset:21024
	ds_read_b128 v[220:223], v175 offset:64
	ds_read_b128 v[224:227], v175 offset:21056
	ds_read_b128 v[228:231], v175 offset:96
	ds_read_b128 v[232:235], v175 offset:21088
	ds_read_b128 v[236:239], v175 offset:128
	ds_read_b128 v[240:243], v175 offset:21120
	s_mov_b32 s8, 0xf149f2ca
	s_waitcnt vmcnt(29) lgkmcnt(9)
	v_mfma_f32_32x32x16_bf16 v[18:33], v[176:179], v[34:37], 0
	ds_read_b128 v[176:179], v175 offset:160
	s_waitcnt vmcnt(28) lgkmcnt(9)
	v_mfma_f32_32x32x16_bf16 v[18:33], v[180:183], v[38:41], v[18:33]
	ds_read_b128 v[180:183], v175 offset:21152
	s_waitcnt lgkmcnt(9)
	v_mfma_f32_32x32x16_bf16 v[2:17], v[184:187], v[34:37], 0
	ds_read_b128 v[184:187], v175 offset:192
	s_waitcnt lgkmcnt(9)
	v_mfma_f32_32x32x16_bf16 v[2:17], v[188:191], v[38:41], v[2:17]
	ds_read_b128 v[188:191], v175 offset:21184
	s_waitcnt vmcnt(27) lgkmcnt(9)
	v_mfma_f32_32x32x16_bf16 v[18:33], v[220:223], v[42:45], v[18:33]
	ds_read_b128 v[220:223], v175 offset:224
	s_waitcnt lgkmcnt(9)
	v_mfma_f32_32x32x16_bf16 v[2:17], v[224:227], v[42:45], v[2:17]
	ds_read_b128 v[224:227], v175 offset:21216
	s_waitcnt vmcnt(26) lgkmcnt(9)
	v_mfma_f32_32x32x16_bf16 v[18:33], v[228:231], v[46:49], v[18:33]
	ds_read_b128 v[228:231], v175 offset:256
	s_waitcnt lgkmcnt(9)
	v_mfma_f32_32x32x16_bf16 v[2:17], v[232:235], v[46:49], v[2:17]
	ds_read_b128 v[232:235], v175 offset:21248
	s_waitcnt vmcnt(25) lgkmcnt(9)
	v_mfma_f32_32x32x16_bf16 v[18:33], v[236:239], v[50:53], v[18:33]
	ds_read_b128 v[236:239], v175 offset:288
	s_waitcnt lgkmcnt(9)
	v_mfma_f32_32x32x16_bf16 v[2:17], v[240:243], v[50:53], v[2:17]
	ds_read_b128 v[240:243], v175 offset:21280
	s_waitcnt vmcnt(24) lgkmcnt(9)
	v_mfma_f32_32x32x16_bf16 v[18:33], v[176:179], v[54:57], v[18:33]
	ds_read_b128 v[176:179], v175 offset:320
	s_waitcnt lgkmcnt(9)
	v_mfma_f32_32x32x16_bf16 v[2:17], v[180:183], v[54:57], v[2:17]
	ds_read_b128 v[180:183], v175 offset:21312
	s_waitcnt vmcnt(23) lgkmcnt(9)
	v_mfma_f32_32x32x16_bf16 v[18:33], v[184:187], v[58:61], v[18:33]
	ds_read_b128 v[184:187], v175 offset:352
	s_waitcnt lgkmcnt(9)
	v_mfma_f32_32x32x16_bf16 v[2:17], v[188:191], v[58:61], v[2:17]
	ds_read_b128 v[188:191], v175 offset:21344
	s_waitcnt vmcnt(22) lgkmcnt(9)
	v_mfma_f32_32x32x16_bf16 v[18:33], v[220:223], v[62:65], v[18:33]
	ds_read_b128 v[220:223], v175 offset:384
	s_waitcnt lgkmcnt(9)
	v_mfma_f32_32x32x16_bf16 v[2:17], v[224:227], v[62:65], v[2:17]
	ds_read_b128 v[224:227], v175 offset:21376
	s_waitcnt vmcnt(21) lgkmcnt(9)
	v_mfma_f32_32x32x16_bf16 v[18:33], v[228:231], v[66:69], v[18:33]
	ds_read_b128 v[228:231], v175 offset:416
	s_waitcnt lgkmcnt(9)
	v_mfma_f32_32x32x16_bf16 v[2:17], v[232:235], v[66:69], v[2:17]
	ds_read_b128 v[232:235], v175 offset:21408
	s_waitcnt vmcnt(20) lgkmcnt(9)
	v_mfma_f32_32x32x16_bf16 v[18:33], v[236:239], v[70:73], v[18:33]
	ds_read_b128 v[236:239], v175 offset:448
	s_waitcnt lgkmcnt(9)
	v_mfma_f32_32x32x16_bf16 v[2:17], v[240:243], v[70:73], v[2:17]
	ds_read_b128 v[240:243], v175 offset:21440
	s_waitcnt vmcnt(19) lgkmcnt(9)
	v_mfma_f32_32x32x16_bf16 v[18:33], v[176:179], v[74:77], v[18:33]
	ds_read_b128 v[176:179], v175 offset:480
	s_waitcnt lgkmcnt(9)
	v_mfma_f32_32x32x16_bf16 v[2:17], v[180:183], v[74:77], v[2:17]
	ds_read_b128 v[180:183], v175 offset:21472
	s_waitcnt vmcnt(18) lgkmcnt(9)
	v_mfma_f32_32x32x16_bf16 v[18:33], v[184:187], v[78:81], v[18:33]
	ds_read_b128 v[184:187], v175 offset:512
	s_waitcnt lgkmcnt(9)
	v_mfma_f32_32x32x16_bf16 v[2:17], v[188:191], v[78:81], v[2:17]
	ds_read_b128 v[188:191], v175 offset:21504
	s_waitcnt vmcnt(17) lgkmcnt(9)
	v_mfma_f32_32x32x16_bf16 v[18:33], v[220:223], v[82:85], v[18:33]
	ds_read_b128 v[220:223], v175 offset:544
	s_waitcnt lgkmcnt(9)
	v_mfma_f32_32x32x16_bf16 v[2:17], v[224:227], v[82:85], v[2:17]
	ds_read_b128 v[224:227], v175 offset:21536
	s_waitcnt vmcnt(16) lgkmcnt(9)
	v_mfma_f32_32x32x16_bf16 v[18:33], v[228:231], v[86:89], v[18:33]
	ds_read_b128 v[228:231], v175 offset:576
	s_waitcnt lgkmcnt(9)
	v_mfma_f32_32x32x16_bf16 v[2:17], v[232:235], v[86:89], v[2:17]
	ds_read_b128 v[232:235], v175 offset:608
	s_waitcnt vmcnt(15) lgkmcnt(9)
	v_mfma_f32_32x32x16_bf16 v[18:33], v[236:239], v[90:93], v[18:33]
	ds_read_b128 v[236:239], v175 offset:21568
	s_waitcnt lgkmcnt(9)
	v_mfma_f32_32x32x16_bf16 v[2:17], v[240:243], v[90:93], v[2:17]
	ds_read_b128 v[240:243], v175 offset:21600
	s_waitcnt vmcnt(14) lgkmcnt(9)
	v_mfma_f32_32x32x16_bf16 v[18:33], v[176:179], v[94:97], v[18:33]
	s_waitcnt lgkmcnt(8)
	v_mfma_f32_32x32x16_bf16 v[2:17], v[180:183], v[94:97], v[2:17]
	s_waitcnt vmcnt(13) lgkmcnt(7)
	v_mfma_f32_32x32x16_bf16 v[18:33], v[184:187], v[98:101], v[18:33]
	s_waitcnt lgkmcnt(6)
	v_mfma_f32_32x32x16_bf16 v[2:17], v[188:191], v[98:101], v[2:17]
	s_waitcnt vmcnt(12) lgkmcnt(5)
	v_mfma_f32_32x32x16_bf16 v[18:33], v[220:223], v[102:105], v[18:33]
	s_waitcnt lgkmcnt(4)
	v_mfma_f32_32x32x16_bf16 v[2:17], v[224:227], v[102:105], v[2:17]
	s_waitcnt vmcnt(11) lgkmcnt(3)
	v_mfma_f32_32x32x16_bf16 v[18:33], v[228:231], v[106:109], v[18:33]
	s_waitcnt vmcnt(10) lgkmcnt(2)
	v_mfma_f32_32x32x16_bf16 v[18:33], v[232:235], v[110:113], v[18:33]
	s_waitcnt lgkmcnt(1)
	v_mfma_f32_32x32x16_bf16 v[2:17], v[236:239], v[106:109], v[2:17]
	s_nop 9
	v_max3_f32 v175, v18, s8, v19
	v_max3_f32 v175, v175, v20, v21
	v_max3_f32 v175, v175, v22, v23
	v_max3_f32 v175, v175, v24, v25
	v_max3_f32 v175, v175, v26, v27
	v_max3_f32 v175, v175, v28, v29
	v_max3_f32 v175, v175, v30, v31
	s_waitcnt lgkmcnt(0)
	v_mfma_f32_32x32x16_bf16 v[2:17], v[240:243], v[110:113], v[2:17]
	v_max3_f32 v175, v175, v32, v33
	v_xor_b32_e32 v176, 32, v192
	v_add_u32_e32 v177, 64, v193
	v_cmp_lt_i32_e32 vcc, v176, v177
	s_and_b32 s8, s29, 4
	s_or_b32 s8, s8, s91
	v_cndmask_b32_e32 v176, v192, v176, vcc
	s_nop 4
	v_max3_f32 v175, v175, v2, v3
	v_max3_f32 v175, v175, v4, v5
	v_max3_f32 v175, v175, v6, v7
	v_max3_f32 v175, v175, v8, v9
	v_max3_f32 v175, v175, v10, v11
	v_max3_f32 v175, v175, v12, v13
	v_max3_f32 v175, v175, v14, v15
	v_max3_f32 v175, v175, v16, v17
	v_lshlrev_b32_e32 v176, 2, v176
	v_mov_b32_e32 v177, v175
	s_mulk_i32 s8, 0x1080
	s_add_i32 s8, s8, 0
	s_add_i32 s8, s8, 0x1ec00
	v_permlane32_swap_b32_e32 v177, v175
	v_max3_f32 v175, v165, v175, v177
	v_sub_f32_e32 v18, v18, v175
	v_exp_f32_e32 v18, v18
	v_sub_f32_e32 v19, v19, v175
	v_exp_f32_e32 v19, v19
	v_sub_f32_e32 v20, v20, v175
	v_exp_f32_e32 v20, v20
	v_sub_f32_e32 v21, v21, v175
	v_exp_f32_e32 v21, v21
	v_sub_f32_e32 v22, v22, v175
	v_add_f32_e32 v177, 0, v18
	v_exp_f32_e32 v22, v22
	v_sub_f32_e32 v23, v23, v175
	v_add_f32_e32 v177, v177, v19
	v_exp_f32_e32 v23, v23
	v_sub_f32_e32 v24, v24, v175
	v_add_f32_e32 v177, v177, v20
	v_exp_f32_e32 v24, v24
	v_sub_f32_e32 v25, v25, v175
	v_add_f32_e32 v177, v177, v21
	v_exp_f32_e32 v25, v25
	v_sub_f32_e32 v26, v26, v175
	v_add_f32_e32 v177, v177, v22
	v_exp_f32_e32 v26, v26
	v_sub_f32_e32 v27, v27, v175
	v_add_f32_e32 v177, v177, v23
	v_exp_f32_e32 v27, v27
	v_sub_f32_e32 v28, v28, v175
	v_add_f32_e32 v177, v177, v24
	v_exp_f32_e32 v28, v28
	v_sub_f32_e32 v29, v29, v175
	v_add_f32_e32 v177, v177, v25
	v_exp_f32_e32 v29, v29
	v_sub_f32_e32 v30, v30, v175
	v_add_f32_e32 v177, v177, v26
	v_exp_f32_e32 v30, v30
	v_sub_f32_e32 v31, v31, v175
	v_add_f32_e32 v177, v177, v27
	v_exp_f32_e32 v31, v31
	v_sub_f32_e32 v32, v32, v175
	v_add_f32_e32 v177, v177, v28
	v_exp_f32_e32 v32, v32
	v_sub_f32_e32 v33, v33, v175
	v_add_f32_e32 v177, v177, v29
	v_exp_f32_e32 v33, v33
	v_sub_f32_e32 v2, v2, v175
	v_add_f32_e32 v177, v177, v30
	v_exp_f32_e32 v178, v2
	v_sub_f32_e32 v2, v3, v175
	v_add_f32_e32 v177, v177, v31
	v_exp_f32_e32 v179, v2
	v_sub_f32_e32 v2, v4, v175
	v_add_f32_e32 v177, v177, v32
	v_exp_f32_e32 v180, v2
	v_sub_f32_e32 v2, v5, v175
	v_add_f32_e32 v177, v177, v33
	v_exp_f32_e32 v5, v2
	v_sub_f32_e32 v3, v6, v175
	v_add_f32_e32 v2, v177, v178
	v_exp_f32_e32 v177, v3
	v_sub_f32_e32 v3, v7, v175
	v_add_f32_e32 v2, v2, v179
	v_exp_f32_e32 v181, v3
	v_sub_f32_e32 v3, v8, v175
	v_add_f32_e32 v2, v2, v180
	v_exp_f32_e32 v182, v3
	v_sub_f32_e32 v3, v9, v175
	v_add_f32_e32 v2, v2, v5
	v_exp_f32_e32 v183, v3
	v_sub_f32_e32 v3, v10, v175
	v_add_f32_e32 v2, v2, v177
	v_exp_f32_e32 v10, v3
	v_sub_f32_e32 v3, v11, v175
	v_add_f32_e32 v2, v2, v181
	v_exp_f32_e32 v11, v3
	v_sub_f32_e32 v3, v12, v175
	v_add_f32_e32 v2, v2, v182
	v_exp_f32_e32 v12, v3
	v_sub_f32_e32 v3, v13, v175
	v_add_f32_e32 v2, v2, v183
	v_exp_f32_e32 v13, v3
	v_sub_f32_e32 v3, v14, v175
	v_add_f32_e32 v2, v2, v10
	v_exp_f32_e32 v14, v3
	v_sub_f32_e32 v3, v15, v175
	v_add_f32_e32 v2, v2, v11
	v_exp_f32_e32 v15, v3
	v_sub_f32_e32 v3, v16, v175
	v_add_f32_e32 v2, v2, v12
	v_exp_f32_e32 v16, v3
	v_sub_f32_e32 v3, v17, v175
	v_add_f32_e32 v2, v2, v13
	v_exp_f32_e32 v17, v3
	v_add_f32_e32 v2, v2, v14
	v_add_f32_e32 v2, v2, v15
	v_add_f32_e32 v2, v2, v16
	v_add_f32_e32 v2, v2, v17
	v_sub_f32_e32 v165, v165, v175
	v_mov_b32_e32 v4, v2
	v_exp_f32_e32 v3, v165
	v_add_u32_e32 v165, s8, v169
	v_permlane32_swap_b32_e32 v4, v2
	v_cvt_pk_bf16_f32 v6, v18, v19
	v_cvt_pk_bf16_f32 v7, v20, v21
	v_cvt_pk_bf16_f32 v8, v22, v23
	v_cvt_pk_bf16_f32 v9, v24, v25
	ds_write_b128 v165, v[6:9]
	v_cvt_pk_bf16_f32 v6, v26, v27
	v_cvt_pk_bf16_f32 v7, v28, v29
	v_cvt_pk_bf16_f32 v8, v30, v31
	v_cvt_pk_bf16_f32 v9, v32, v33
	ds_write_b128 v165, v[6:9] offset:1024
	v_cvt_pk_bf16_f32 v6, v178, v179
	v_cvt_pk_bf16_f32 v7, v180, v5
	v_cvt_pk_bf16_f32 v8, v177, v181
	v_cvt_pk_bf16_f32 v9, v182, v183
	ds_write_b128 v165, v[6:9] offset:2048
	v_cvt_pk_bf16_f32 v6, v10, v11
	v_cvt_pk_bf16_f32 v7, v12, v13
	v_cvt_pk_bf16_f32 v8, v14, v15
	v_cvt_pk_bf16_f32 v9, v16, v17
	ds_write_b128 v165, v[6:9] offset:3072
	s_and_saveexec_b64 s[16:17], s[4:5]
	v_add_u32_e32 v5, s8, v171
	ds_write_b32 v5, v3 offset:4096
	s_or_b64 exec, exec, s[16:17]
	s_waitcnt lgkmcnt(4)
	v_add_f32_e32 v2, v2, v4
	v_fmac_f32_e32 v2, v0, v3
	v_mov_b32_e32 v0, v2
	s_branch .LBB0_414
